# per-sweep constants (second-MFMA weight operand, thresholds) computed once per sweep instead of per chunk
# baseline (speedup 1.0000x reference)
; template <int PASS> ...
;     ...
;         for (int e = 0; e < 8; ++e) { const unsigned char* tp = lp + (hb * 8 + e) * 2048; kf[e][0] = *(const h16x8*)(tp + ((fq ^ sw) << 4)); kf[e][1] = *(const h16x8*)(tp + (((fq + 4) ^ sw) << 4)); }
; #pragma unroll
;         for (int e = 0; e < 8; ++e) { const int T = Tbase + hb * 8 + e;
;             f32x4 a0 = (f32x4){0.f, 0.f, 0.f, 0.f}, a1 = a0;
;             a0 = __builtin_amdgcn_mfma_f32_16x16x32_f16(aq[0][0], kf[e][0], a0, 0, 0, 0); a0 = __builtin_amdgcn_mfma_f32_16x16x32_f16(aq[0][1], kf[e][1], a0, 0, 0, 0);
;             a1 = __builtin_amdgcn_mfma_f32_16x16x32_f16(aq[1][0], kf[e][0], a1, 0, 0, 0); a1 = __builtin_amdgcn_mfma_f32_16x16x32_f16(aq[1][1], kf[e][1], a1, 0, 0, 0);
;             const h16x2 z2 = (h16x2){(h16)0.f, (h16)0.f};
;             const h16x2 r0 = __builtin_elementwise_max(__builtin_bit_cast(h16x2, __builtin_amdgcn_cvt_pkrtz(a0[0], a0[1])), z2), r1 = __builtin_elementwise_max(__builtin_bit_cast(h16x2, __builtin_amdgcn_cvt_pkrtz(a0[2], a0[3])), z2);
;             const h16x2 r2 = __builtin_elementwise_max(__builtin_bit_cast(h16x2, __builtin_amdgcn_cvt_pkrtz(a1[0], a1[1])), z2), r3 = __builtin_elementwise_max(__builtin_bit_cast(h16x2, __builtin_amdgcn_cvt_pkrtz(a1[2], a1[3])), z2);
;             const float sa = __builtin_amdgcn_fdot2(r0, wp[0], __builtin_amdgcn_fdot2(r1, wp[1], __builtin_amdgcn_fdot2(r2, wp[2], __builtin_amdgcn_fdot2(r3, wp[3], 0.f, false), false), false), false);
;             const int key = 16 * T + fr;
;             if (key <= tq) {
;                 const unsigned bin = (unsigned)(int)fminf(fmaxf(sa * 32.f + 128.f, 0.f), 255.f);
;                 if (PASS == 1) { if (bin >= b0) atomicAdd(&myhist[fq * 256 + bin], 1u); }
; __device__ __forceinline__ void dsa_select(const h16* PROJ, unsigned short* IDX, int* CNT, unsigned char* shm, unsigned* bar, unsigned xcc, unsigned xrank) {
;     ...
;             float wv[8];
;             { const h16x8 w8 = *(const h16x8*)(PROJ + O_WI + (size_t)(tokbase + tq) * 8);
; #pragma unroll
;               for (int h = 0; h < 8; ++h) wv[h] = (float)w8[h] * 0.04419417382415922f; }
;             h16x2 wp[4];
; #pragma unroll
;             for (int h = 0; h < 4; ++h) { wp[h].x = (h16)wv[(h >> 1) * 4 + (h & 1) * 2]; wp[h].y = (h16)wv[(h >> 1) * 4 + (h & 1) * 2 + 1]; }
.LBB0_182:
	s_and_b32 s62, s4, 0x8000
	v_add_u32_e32 v64, s62, v134
	v_add_u32_e32 v122, v64, v135
	v_add_u32_e32 v123, v64, v136
	v_lshlrev_b32_e32 v121, 8, v121
	v_sub_u32_e32 v121, v115, v121
	v_sub_u32_e32 v78, v192, v121
	s_cmp_lg_u32 s64, 0
	s_cbranch_scc1 .Lp1_skipw
	v_mov_b32_e32 v79, 0x437f0000
	v_mul_f32_e32 v88, v106, v106
	v_fmac_f32_e32 v88, v107, v107
	v_fmac_f32_e32 v88, v108, v108
	v_fmac_f32_e32 v88, v109, v109
	v_fmac_f32_e32 v88, v110, v110
	v_fmac_f32_e32 v88, v111, v111
	v_fmac_f32_e32 v88, v112, v112
	v_fmac_f32_e32 v88, v113, v113
	v_max_f32_e32 v88, 0x358637bd, v88
	v_rsq_f32_e32 v88, v88
	s_mov_b32 s62, 0x100001
	s_mov_b32 s63, 0x10000100
	v_mul_f32_e32 v88, 4.0, v88
	v_cvt_pkrtz_f16_f32 v88, v88, v88
	v_pk_mul_f16 v80, v193, v88
	v_pk_mul_f16 v81, v194, v88
	v_pk_mul_f16 v82, v195, v88
	v_pk_mul_f16 v83, v196, v88
	v_cndmask_b32_e64 v80, 0, v80, s[62:63]
	v_cndmask_b32_e64 v81, 0, v81, s[62:63]
	v_cndmask_b32_e64 v82, 0, v82, s[62:63]
	v_cndmask_b32_e64 v83, 0, v83, s[62:63]
	v_mov_b32_e32 v84, 0x43000000
	v_mov_b32_e32 v85, 0
	v_mov_b32_e32 v86, 0
	v_mov_b32_e32 v87, 0
.Lp1_skipw:
	v_cmp_le_i32_e32 vcc, 0, v78
	s_cmp_eq_u64 vcc, -1
	s_cbranch_scc1 .Lp1_interior
	ds_read_b128 v[32:35], v122
	ds_read_b128 v[36:39], v123
	ds_read_b128 v[40:43], v122 offset:2048
	ds_read_b128 v[44:47], v123 offset:2048
	s_waitcnt lgkmcnt(2)
	v_mfma_f32_16x16x32_f16 v[48:51], v[0:3], v[32:35], 0
	v_mfma_f32_16x16x32_f16 v[52:55], v[8:11], v[32:35], 0
	v_mfma_f32_16x16x32_f16 v[48:51], v[4:7], v[36:39], v[48:51]
	v_mfma_f32_16x16x32_f16 v[52:55], v[12:15], v[36:39], v[52:55]
	s_nop 3
	ds_read_b128 v[32:35], v122 offset:4096
	ds_read_b128 v[36:39], v123 offset:4096
	s_waitcnt lgkmcnt(2)
	v_mfma_f32_16x16x32_f16 v[56:59], v[0:3], v[40:43], 0
	v_cvt_pkrtz_f16_f32 v67, v54, v55
	v_cvt_pkrtz_f16_f32 v66, v52, v53
	v_pk_max_f16 v67, v67, 0
	v_pk_max_f16 v66, v66, 0
	v_mfma_f32_16x16x32_f16 v[60:63], v[8:11], v[40:43], 0
	v_cvt_pkrtz_f16_f32 v65, v50, v51
	v_cvt_pkrtz_f16_f32 v64, v48, v49
	v_pk_max_f16 v65, v65, 0
	v_mfma_f32_16x16x32_f16 v[56:59], v[4:7], v[44:47], v[56:59]
	v_pk_max_f16 v64, v64, 0
	v_mfma_f32_16x16x32_f16 v[60:63], v[12:15], v[44:47], v[60:63]
	s_nop 3
	v_mfma_f32_16x16x32_f16 v[68:71], v[80:83], v[64:67], v[84:87]
	ds_read_b128 v[40:43], v122 offset:6144
	ds_read_b128 v[44:47], v123 offset:6144
	s_waitcnt lgkmcnt(2)
	v_mfma_f32_16x16x32_f16 v[48:51], v[0:3], v[32:35], 0
	v_cvt_pkrtz_f16_f32 v67, v62, v63
	v_cvt_pkrtz_f16_f32 v66, v60, v61
	v_pk_max_f16 v67, v67, 0
	v_pk_max_f16 v66, v66, 0
	v_mfma_f32_16x16x32_f16 v[52:55], v[8:11], v[32:35], 0
	v_cvt_pkrtz_f16_f32 v65, v58, v59
	v_cvt_pkrtz_f16_f32 v64, v56, v57
	v_med3_f32 v76, v68, 0, v79
	v_pk_max_f16 v65, v65, 0
	v_mfma_f32_16x16x32_f16 v[48:51], v[4:7], v[36:39], v[48:51]
	v_pk_max_f16 v64, v64, 0
	v_cvt_u32_f32_e32 v76, v76
	v_cmp_le_i32_e32 vcc, -240, v78
	v_mfma_f32_16x16x32_f16 v[52:55], v[12:15], v[36:39], v[52:55]
	v_lshl_add_u32 v77, v76, 2, v139
	s_and_b64 exec, exec, vcc
	ds_add_u32 v77, v212
	s_mov_b64 exec, -1
	v_mfma_f32_16x16x32_f16 v[72:75], v[80:83], v[64:67], v[84:87]
	ds_read_b128 v[32:35], v122 offset:8192
	ds_read_b128 v[36:39], v123 offset:8192
	s_waitcnt lgkmcnt(3)
	v_mfma_f32_16x16x32_f16 v[56:59], v[0:3], v[40:43], 0
	v_cvt_pkrtz_f16_f32 v67, v54, v55
	v_cvt_pkrtz_f16_f32 v66, v52, v53
	v_pk_max_f16 v67, v67, 0
	v_pk_max_f16 v66, v66, 0
	v_mfma_f32_16x16x32_f16 v[60:63], v[8:11], v[40:43], 0
	v_cvt_pkrtz_f16_f32 v65, v50, v51
	v_cvt_pkrtz_f16_f32 v64, v48, v49
	v_med3_f32 v76, v72, 0, v79
	v_pk_max_f16 v65, v65, 0
	v_mfma_f32_16x16x32_f16 v[56:59], v[4:7], v[44:47], v[56:59]
	v_pk_max_f16 v64, v64, 0
	v_cvt_u32_f32_e32 v76, v76
	v_cmp_le_i32_e32 vcc, -224, v78
	v_mfma_f32_16x16x32_f16 v[60:63], v[12:15], v[44:47], v[60:63]
	v_lshl_add_u32 v77, v76, 2, v139
	s_and_b64 exec, exec, vcc
	ds_add_u32 v77, v212
	s_mov_b64 exec, -1
	v_mfma_f32_16x16x32_f16 v[68:71], v[80:83], v[64:67], v[84:87]
	ds_read_b128 v[40:43], v122 offset:10240
	ds_read_b128 v[44:47], v123 offset:10240
	s_waitcnt lgkmcnt(3)
	v_mfma_f32_16x16x32_f16 v[48:51], v[0:3], v[32:35], 0
	v_cvt_pkrtz_f16_f32 v67, v62, v63
	v_cvt_pkrtz_f16_f32 v66, v60, v61
	v_pk_max_f16 v67, v67, 0
	v_pk_max_f16 v66, v66, 0
	v_mfma_f32_16x16x32_f16 v[52:55], v[8:11], v[32:35], 0
	v_cvt_pkrtz_f16_f32 v65, v58, v59
	v_cvt_pkrtz_f16_f32 v64, v56, v57
	v_med3_f32 v76, v68, 0, v79
	v_pk_max_f16 v65, v65, 0
	v_mfma_f32_16x16x32_f16 v[48:51], v[4:7], v[36:39], v[48:51]
	v_pk_max_f16 v64, v64, 0
	v_cvt_u32_f32_e32 v76, v76
	v_cmp_le_i32_e32 vcc, -208, v78
	v_mfma_f32_16x16x32_f16 v[52:55], v[12:15], v[36:39], v[52:55]
	v_lshl_add_u32 v77, v76, 2, v139
	s_and_b64 exec, exec, vcc
	ds_add_u32 v77, v212
	s_mov_b64 exec, -1
	v_mfma_f32_16x16x32_f16 v[72:75], v[80:83], v[64:67], v[84:87]
	ds_read_b128 v[32:35], v122 offset:12288
	ds_read_b128 v[36:39], v123 offset:12288
	s_waitcnt lgkmcnt(3)
	v_mfma_f32_16x16x32_f16 v[56:59], v[0:3], v[40:43], 0
	v_cvt_pkrtz_f16_f32 v67, v54, v55
	v_cvt_pkrtz_f16_f32 v66, v52, v53
	v_pk_max_f16 v67, v67, 0
	v_pk_max_f16 v66, v66, 0
	v_mfma_f32_16x16x32_f16 v[60:63], v[8:11], v[40:43], 0
	v_cvt_pkrtz_f16_f32 v65, v50, v51
	v_cvt_pkrtz_f16_f32 v64, v48, v49
	v_med3_f32 v76, v72, 0, v79
	v_pk_max_f16 v65, v65, 0
	v_mfma_f32_16x16x32_f16 v[56:59], v[4:7], v[44:47], v[56:59]
	v_pk_max_f16 v64, v64, 0
	v_cvt_u32_f32_e32 v76, v76
	v_cmp_le_i32_e32 vcc, -192, v78
	v_mfma_f32_16x16x32_f16 v[60:63], v[12:15], v[44:47], v[60:63]
	v_lshl_add_u32 v77, v76, 2, v139
	s_and_b64 exec, exec, vcc
	ds_add_u32 v77, v212
	s_mov_b64 exec, -1
	v_mfma_f32_16x16x32_f16 v[68:71], v[80:83], v[64:67], v[84:87]
	ds_read_b128 v[40:43], v122 offset:14336
	ds_read_b128 v[44:47], v123 offset:14336
	s_waitcnt lgkmcnt(3)
; template <int PASS> ...
;     ...
;         for (int e = 0; e < 8; ++e) { const unsigned char* tp = lp + (hb * 8 + e) * 2048; kf[e][0] = *(const h16x8*)(tp + ((fq ^ sw) << 4)); kf[e][1] = *(const h16x8*)(tp + (((fq + 4) ^ sw) << 4)); }
; #pragma unroll
;         for (int e = 0; e < 8; ++e) { const int T = Tbase + hb * 8 + e;
;             f32x4 a0 = (f32x4){0.f, 0.f, 0.f, 0.f}, a1 = a0;
;             a0 = __builtin_amdgcn_mfma_f32_16x16x32_f16(aq[0][0], kf[e][0], a0, 0, 0, 0); a0 = __builtin_amdgcn_mfma_f32_16x16x32_f16(aq[0][1], kf[e][1], a0, 0, 0, 0);
;             a1 = __builtin_amdgcn_mfma_f32_16x16x32_f16(aq[1][0], kf[e][0], a1, 0, 0, 0); a1 = __builtin_amdgcn_mfma_f32_16x16x32_f16(aq[1][1], kf[e][1], a1, 0, 0, 0);
;             const h16x2 z2 = (h16x2){(h16)0.f, (h16)0.f};
;             const h16x2 r0 = __builtin_elementwise_max(__builtin_bit_cast(h16x2, __builtin_amdgcn_cvt_pkrtz(a0[0], a0[1])), z2), r1 = __builtin_elementwise_max(__builtin_bit_cast(h16x2, __builtin_amdgcn_cvt_pkrtz(a0[2], a0[3])), z2);
;             const h16x2 r2 = __builtin_elementwise_max(__builtin_bit_cast(h16x2, __builtin_amdgcn_cvt_pkrtz(a1[0], a1[1])), z2), r3 = __builtin_elementwise_max(__builtin_bit_cast(h16x2, __builtin_amdgcn_cvt_pkrtz(a1[2], a1[3])), z2);
;             const float sa = __builtin_amdgcn_fdot2(r0, wp[0], __builtin_amdgcn_fdot2(r1, wp[1], __builtin_amdgcn_fdot2(r2, wp[2], __builtin_amdgcn_fdot2(r3, wp[3], 0.f, false), false), false), false);
;             const int key = 16 * T + fr;
;             if (key <= tq) {
;                 const unsigned bin = (unsigned)(int)fminf(fmaxf(sa * 32.f + 128.f, 0.f), 255.f);
;                 if (PASS == 1) { if (bin >= b0) atomicAdd(&myhist[fq * 256 + bin], 1u); }
	v_mfma_f32_16x16x32_f16 v[48:51], v[0:3], v[32:35], 0
	v_cvt_pkrtz_f16_f32 v67, v62, v63
	v_cvt_pkrtz_f16_f32 v66, v60, v61
	v_pk_max_f16 v67, v67, 0
	v_pk_max_f16 v66, v66, 0
	v_mfma_f32_16x16x32_f16 v[52:55], v[8:11], v[32:35], 0
	v_cvt_pkrtz_f16_f32 v65, v58, v59
	v_cvt_pkrtz_f16_f32 v64, v56, v57
	v_med3_f32 v76, v68, 0, v79
	v_pk_max_f16 v65, v65, 0
	v_mfma_f32_16x16x32_f16 v[48:51], v[4:7], v[36:39], v[48:51]
	v_pk_max_f16 v64, v64, 0
	v_cvt_u32_f32_e32 v76, v76
	v_cmp_le_i32_e32 vcc, -176, v78
	v_mfma_f32_16x16x32_f16 v[52:55], v[12:15], v[36:39], v[52:55]
	v_lshl_add_u32 v77, v76, 2, v139
	s_and_b64 exec, exec, vcc
	ds_add_u32 v77, v212
	s_mov_b64 exec, -1
	v_mfma_f32_16x16x32_f16 v[72:75], v[80:83], v[64:67], v[84:87]
	ds_read_b128 v[32:35], v122 offset:16384
	ds_read_b128 v[36:39], v123 offset:16384
	s_waitcnt lgkmcnt(3)
	v_mfma_f32_16x16x32_f16 v[56:59], v[0:3], v[40:43], 0
	v_cvt_pkrtz_f16_f32 v67, v54, v55
	v_cvt_pkrtz_f16_f32 v66, v52, v53
	v_pk_max_f16 v67, v67, 0
	v_pk_max_f16 v66, v66, 0
	v_mfma_f32_16x16x32_f16 v[60:63], v[8:11], v[40:43], 0
	v_cvt_pkrtz_f16_f32 v65, v50, v51
	v_cvt_pkrtz_f16_f32 v64, v48, v49
	v_med3_f32 v76, v72, 0, v79
	v_pk_max_f16 v65, v65, 0
	v_mfma_f32_16x16x32_f16 v[56:59], v[4:7], v[44:47], v[56:59]
	v_pk_max_f16 v64, v64, 0
	v_cvt_u32_f32_e32 v76, v76
	v_cmp_le_i32_e32 vcc, -160, v78
	v_mfma_f32_16x16x32_f16 v[60:63], v[12:15], v[44:47], v[60:63]
	v_lshl_add_u32 v77, v76, 2, v139
	s_and_b64 exec, exec, vcc
	ds_add_u32 v77, v212
	s_mov_b64 exec, -1
	v_mfma_f32_16x16x32_f16 v[68:71], v[80:83], v[64:67], v[84:87]
	ds_read_b128 v[40:43], v122 offset:18432
	ds_read_b128 v[44:47], v123 offset:18432
	s_waitcnt lgkmcnt(3)
	v_mfma_f32_16x16x32_f16 v[48:51], v[0:3], v[32:35], 0
	v_cvt_pkrtz_f16_f32 v67, v62, v63
	v_cvt_pkrtz_f16_f32 v66, v60, v61
	v_pk_max_f16 v67, v67, 0
	v_pk_max_f16 v66, v66, 0
	v_mfma_f32_16x16x32_f16 v[52:55], v[8:11], v[32:35], 0
	v_cvt_pkrtz_f16_f32 v65, v58, v59
	v_cvt_pkrtz_f16_f32 v64, v56, v57
	v_med3_f32 v76, v68, 0, v79
	v_pk_max_f16 v65, v65, 0
	v_mfma_f32_16x16x32_f16 v[48:51], v[4:7], v[36:39], v[48:51]
	v_pk_max_f16 v64, v64, 0
	v_cvt_u32_f32_e32 v76, v76
	v_cmp_le_i32_e32 vcc, -144, v78
	v_mfma_f32_16x16x32_f16 v[52:55], v[12:15], v[36:39], v[52:55]
	v_lshl_add_u32 v77, v76, 2, v139
	s_and_b64 exec, exec, vcc
	ds_add_u32 v77, v212
	s_mov_b64 exec, -1
	v_mfma_f32_16x16x32_f16 v[72:75], v[80:83], v[64:67], v[84:87]
	ds_read_b128 v[32:35], v122 offset:20480
	ds_read_b128 v[36:39], v123 offset:20480
	s_waitcnt lgkmcnt(3)
	v_mfma_f32_16x16x32_f16 v[56:59], v[0:3], v[40:43], 0
	v_cvt_pkrtz_f16_f32 v67, v54, v55
	v_cvt_pkrtz_f16_f32 v66, v52, v53
	v_pk_max_f16 v67, v67, 0
	v_pk_max_f16 v66, v66, 0
	v_mfma_f32_16x16x32_f16 v[60:63], v[8:11], v[40:43], 0
	v_cvt_pkrtz_f16_f32 v65, v50, v51
	v_cvt_pkrtz_f16_f32 v64, v48, v49
	v_med3_f32 v76, v72, 0, v79
	v_pk_max_f16 v65, v65, 0
	v_mfma_f32_16x16x32_f16 v[56:59], v[4:7], v[44:47], v[56:59]
	v_pk_max_f16 v64, v64, 0
	v_cvt_u32_f32_e32 v76, v76
	v_cmp_le_i32_e32 vcc, -128, v78
	v_mfma_f32_16x16x32_f16 v[60:63], v[12:15], v[44:47], v[60:63]
	v_lshl_add_u32 v77, v76, 2, v139
	s_and_b64 exec, exec, vcc
	ds_add_u32 v77, v212
	s_mov_b64 exec, -1
	v_mfma_f32_16x16x32_f16 v[68:71], v[80:83], v[64:67], v[84:87]
	ds_read_b128 v[40:43], v122 offset:22528
	ds_read_b128 v[44:47], v123 offset:22528
	s_waitcnt lgkmcnt(3)
	v_mfma_f32_16x16x32_f16 v[48:51], v[0:3], v[32:35], 0
	v_cvt_pkrtz_f16_f32 v67, v62, v63
	v_cvt_pkrtz_f16_f32 v66, v60, v61
	v_pk_max_f16 v67, v67, 0
	v_pk_max_f16 v66, v66, 0
	v_mfma_f32_16x16x32_f16 v[52:55], v[8:11], v[32:35], 0
	v_cvt_pkrtz_f16_f32 v65, v58, v59
	v_cvt_pkrtz_f16_f32 v64, v56, v57
	v_med3_f32 v76, v68, 0, v79
	v_pk_max_f16 v65, v65, 0
	v_mfma_f32_16x16x32_f16 v[48:51], v[4:7], v[36:39], v[48:51]
	v_pk_max_f16 v64, v64, 0
	v_cvt_u32_f32_e32 v76, v76
	v_cmp_le_i32_e32 vcc, -112, v78
	v_mfma_f32_16x16x32_f16 v[52:55], v[12:15], v[36:39], v[52:55]
	v_lshl_add_u32 v77, v76, 2, v139
	s_and_b64 exec, exec, vcc
	ds_add_u32 v77, v212
	s_mov_b64 exec, -1
	v_mfma_f32_16x16x32_f16 v[72:75], v[80:83], v[64:67], v[84:87]
	ds_read_b128 v[32:35], v122 offset:24576
	ds_read_b128 v[36:39], v123 offset:24576
	s_waitcnt lgkmcnt(3)
	v_mfma_f32_16x16x32_f16 v[56:59], v[0:3], v[40:43], 0
	v_cvt_pkrtz_f16_f32 v67, v54, v55
	v_cvt_pkrtz_f16_f32 v66, v52, v53
	v_pk_max_f16 v67, v67, 0
	v_pk_max_f16 v66, v66, 0
	v_mfma_f32_16x16x32_f16 v[60:63], v[8:11], v[40:43], 0
	v_cvt_pkrtz_f16_f32 v65, v50, v51
	v_cvt_pkrtz_f16_f32 v64, v48, v49
	v_med3_f32 v76, v72, 0, v79
	v_pk_max_f16 v65, v65, 0
	v_mfma_f32_16x16x32_f16 v[56:59], v[4:7], v[44:47], v[56:59]
	v_pk_max_f16 v64, v64, 0
	v_cvt_u32_f32_e32 v76, v76
	v_cmp_le_i32_e32 vcc, -96, v78
	v_mfma_f32_16x16x32_f16 v[60:63], v[12:15], v[44:47], v[60:63]
	v_lshl_add_u32 v77, v76, 2, v139
	s_and_b64 exec, exec, vcc
	ds_add_u32 v77, v212
	s_mov_b64 exec, -1
	v_mfma_f32_16x16x32_f16 v[68:71], v[80:83], v[64:67], v[84:87]
	ds_read_b128 v[40:43], v122 offset:26624
	ds_read_b128 v[44:47], v123 offset:26624
	s_waitcnt lgkmcnt(3)
	v_mfma_f32_16x16x32_f16 v[48:51], v[0:3], v[32:35], 0
	v_cvt_pkrtz_f16_f32 v67, v62, v63
	v_cvt_pkrtz_f16_f32 v66, v60, v61
	v_pk_max_f16 v67, v67, 0
	v_pk_max_f16 v66, v66, 0
	v_mfma_f32_16x16x32_f16 v[52:55], v[8:11], v[32:35], 0
	v_cvt_pkrtz_f16_f32 v65, v58, v59
	v_cvt_pkrtz_f16_f32 v64, v56, v57
	v_med3_f32 v76, v68, 0, v79
	v_pk_max_f16 v65, v65, 0
	v_mfma_f32_16x16x32_f16 v[48:51], v[4:7], v[36:39], v[48:51]
	v_pk_max_f16 v64, v64, 0
	v_cvt_u32_f32_e32 v76, v76
	v_cmp_le_i32_e32 vcc, -80, v78
	v_mfma_f32_16x16x32_f16 v[52:55], v[12:15], v[36:39], v[52:55]
	v_lshl_add_u32 v77, v76, 2, v139
	s_and_b64 exec, exec, vcc
	ds_add_u32 v77, v212
	s_mov_b64 exec, -1
	v_mfma_f32_16x16x32_f16 v[72:75], v[80:83], v[64:67], v[84:87]
	ds_read_b128 v[32:35], v122 offset:28672
	ds_read_b128 v[36:39], v123 offset:28672
	s_waitcnt lgkmcnt(3)
; template <int PASS> ...
;     ...
;         for (int e = 0; e < 8; ++e) { const unsigned char* tp = lp + (hb * 8 + e) * 2048; kf[e][0] = *(const h16x8*)(tp + ((fq ^ sw) << 4)); kf[e][1] = *(const h16x8*)(tp + (((fq + 4) ^ sw) << 4)); }
; #pragma unroll
;         for (int e = 0; e < 8; ++e) { const int T = Tbase + hb * 8 + e;
;             f32x4 a0 = (f32x4){0.f, 0.f, 0.f, 0.f}, a1 = a0;
;             a0 = __builtin_amdgcn_mfma_f32_16x16x32_f16(aq[0][0], kf[e][0], a0, 0, 0, 0); a0 = __builtin_amdgcn_mfma_f32_16x16x32_f16(aq[0][1], kf[e][1], a0, 0, 0, 0);
;             a1 = __builtin_amdgcn_mfma_f32_16x16x32_f16(aq[1][0], kf[e][0], a1, 0, 0, 0); a1 = __builtin_amdgcn_mfma_f32_16x16x32_f16(aq[1][1], kf[e][1], a1, 0, 0, 0);
;             const h16x2 z2 = (h16x2){(h16)0.f, (h16)0.f};
;             const h16x2 r0 = __builtin_elementwise_max(__builtin_bit_cast(h16x2, __builtin_amdgcn_cvt_pkrtz(a0[0], a0[1])), z2), r1 = __builtin_elementwise_max(__builtin_bit_cast(h16x2, __builtin_amdgcn_cvt_pkrtz(a0[2], a0[3])), z2);
;             const h16x2 r2 = __builtin_elementwise_max(__builtin_bit_cast(h16x2, __builtin_amdgcn_cvt_pkrtz(a1[0], a1[1])), z2), r3 = __builtin_elementwise_max(__builtin_bit_cast(h16x2, __builtin_amdgcn_cvt_pkrtz(a1[2], a1[3])), z2);
;             const float sa = __builtin_amdgcn_fdot2(r0, wp[0], __builtin_amdgcn_fdot2(r1, wp[1], __builtin_amdgcn_fdot2(r2, wp[2], __builtin_amdgcn_fdot2(r3, wp[3], 0.f, false), false), false), false);
;             const int key = 16 * T + fr;
;             if (key <= tq) {
;                 const unsigned bin = (unsigned)(int)fminf(fmaxf(sa * 32.f + 128.f, 0.f), 255.f);
;                 if (PASS == 1) { if (bin >= b0) atomicAdd(&myhist[fq * 256 + bin], 1u); }
; __device__ __forceinline__ void dsa_select(const h16* PROJ, unsigned short* IDX, int* CNT, unsigned char* shm, unsigned* bar, unsigned xcc, unsigned xrank) {
;     ...
;             float wv[8];
;             { const h16x8 w8 = *(const h16x8*)(PROJ + O_WI + (size_t)(tokbase + tq) * 8);
; #pragma unroll
;               for (int h = 0; h < 8; ++h) wv[h] = (float)w8[h] * 0.04419417382415922f; }
;             h16x2 wp[4];
; #pragma unroll
;             for (int h = 0; h < 4; ++h) { wp[h].x = (h16)wv[(h >> 1) * 4 + (h & 1) * 2]; wp[h].y = (h16)wv[(h >> 1) * 4 + (h & 1) * 2 + 1]; }
	v_mfma_f32_16x16x32_f16 v[56:59], v[0:3], v[40:43], 0
	v_cvt_pkrtz_f16_f32 v67, v54, v55
	v_cvt_pkrtz_f16_f32 v66, v52, v53
	v_pk_max_f16 v67, v67, 0
	v_pk_max_f16 v66, v66, 0
	v_mfma_f32_16x16x32_f16 v[60:63], v[8:11], v[40:43], 0
	v_cvt_pkrtz_f16_f32 v65, v50, v51
	v_cvt_pkrtz_f16_f32 v64, v48, v49
	v_med3_f32 v76, v72, 0, v79
	v_pk_max_f16 v65, v65, 0
	v_mfma_f32_16x16x32_f16 v[56:59], v[4:7], v[44:47], v[56:59]
	v_pk_max_f16 v64, v64, 0
	v_cvt_u32_f32_e32 v76, v76
	v_cmp_le_i32_e32 vcc, -64, v78
	v_mfma_f32_16x16x32_f16 v[60:63], v[12:15], v[44:47], v[60:63]
	v_lshl_add_u32 v77, v76, 2, v139
	s_and_b64 exec, exec, vcc
	ds_add_u32 v77, v212
	s_mov_b64 exec, -1
	v_mfma_f32_16x16x32_f16 v[68:71], v[80:83], v[64:67], v[84:87]
	ds_read_b128 v[40:43], v122 offset:30720
	ds_read_b128 v[44:47], v123 offset:30720
	s_waitcnt lgkmcnt(3)
	v_mfma_f32_16x16x32_f16 v[48:51], v[0:3], v[32:35], 0
	v_cvt_pkrtz_f16_f32 v67, v62, v63
	v_cvt_pkrtz_f16_f32 v66, v60, v61
	v_pk_max_f16 v67, v67, 0
	v_pk_max_f16 v66, v66, 0
	v_mfma_f32_16x16x32_f16 v[52:55], v[8:11], v[32:35], 0
	v_cvt_pkrtz_f16_f32 v65, v58, v59
	v_cvt_pkrtz_f16_f32 v64, v56, v57
	v_med3_f32 v76, v68, 0, v79
	v_pk_max_f16 v65, v65, 0
	v_mfma_f32_16x16x32_f16 v[48:51], v[4:7], v[36:39], v[48:51]
	v_pk_max_f16 v64, v64, 0
	v_cvt_u32_f32_e32 v76, v76
	v_cmp_le_i32_e32 vcc, -48, v78
	v_mfma_f32_16x16x32_f16 v[52:55], v[12:15], v[36:39], v[52:55]
	v_lshl_add_u32 v77, v76, 2, v139
	s_and_b64 exec, exec, vcc
	ds_add_u32 v77, v212
	s_mov_b64 exec, -1
	v_mfma_f32_16x16x32_f16 v[72:75], v[80:83], v[64:67], v[84:87]
	s_nop 3
	s_waitcnt lgkmcnt(1)
	v_mfma_f32_16x16x32_f16 v[56:59], v[0:3], v[40:43], 0
	v_cvt_pkrtz_f16_f32 v67, v54, v55
	v_cvt_pkrtz_f16_f32 v66, v52, v53
	v_pk_max_f16 v67, v67, 0
	v_pk_max_f16 v66, v66, 0
	v_mfma_f32_16x16x32_f16 v[60:63], v[8:11], v[40:43], 0
	v_cvt_pkrtz_f16_f32 v65, v50, v51
	v_cvt_pkrtz_f16_f32 v64, v48, v49
	v_med3_f32 v76, v72, 0, v79
	v_pk_max_f16 v65, v65, 0
	v_mfma_f32_16x16x32_f16 v[56:59], v[4:7], v[44:47], v[56:59]
	v_pk_max_f16 v64, v64, 0
	v_cvt_u32_f32_e32 v76, v76
	v_cmp_le_i32_e32 vcc, -32, v78
	v_mfma_f32_16x16x32_f16 v[60:63], v[12:15], v[44:47], v[60:63]
	v_lshl_add_u32 v77, v76, 2, v139
	s_and_b64 exec, exec, vcc
	ds_add_u32 v77, v212
	s_mov_b64 exec, -1
	v_mfma_f32_16x16x32_f16 v[68:71], v[80:83], v[64:67], v[84:87]
	s_nop 3
	v_cvt_pkrtz_f16_f32 v67, v62, v63
	v_cvt_pkrtz_f16_f32 v66, v60, v61
	v_pk_max_f16 v67, v67, 0
	v_pk_max_f16 v66, v66, 0
	v_cvt_pkrtz_f16_f32 v65, v58, v59
	v_cvt_pkrtz_f16_f32 v64, v56, v57
	v_med3_f32 v76, v68, 0, v79
	v_pk_max_f16 v65, v65, 0
	v_pk_max_f16 v64, v64, 0
	v_cvt_u32_f32_e32 v76, v76
	v_cmp_le_i32_e32 vcc, -16, v78
	v_lshl_add_u32 v77, v76, 2, v139
	s_and_b64 exec, exec, vcc
	ds_add_u32 v77, v212
	s_mov_b64 exec, -1
	v_mfma_f32_16x16x32_f16 v[72:75], v[80:83], v[64:67], v[84:87]
	s_nop 7
	s_nop 3
	v_med3_f32 v76, v72, 0, v79
	v_cvt_u32_f32_e32 v76, v76
	v_cmp_le_i32_e32 vcc, 0, v78
	v_lshl_add_u32 v77, v76, 2, v139
	s_and_b64 exec, exec, vcc
	ds_add_u32 v77, v212
	s_mov_b64 exec, -1
	s_branch .LBB0_239
.Lp1_interior:
	ds_read_b128 v[32:35], v122
	ds_read_b128 v[36:39], v123
	ds_read_b128 v[40:43], v122 offset:2048
	ds_read_b128 v[44:47], v123 offset:2048
	s_waitcnt lgkmcnt(2)
	v_mfma_f32_16x16x32_f16 v[48:51], v[0:3], v[32:35], 0
	v_mfma_f32_16x16x32_f16 v[52:55], v[8:11], v[32:35], 0
	v_mfma_f32_16x16x32_f16 v[48:51], v[4:7], v[36:39], v[48:51]
	v_mfma_f32_16x16x32_f16 v[52:55], v[12:15], v[36:39], v[52:55]
	s_nop 3
	ds_read_b128 v[32:35], v122 offset:4096
	ds_read_b128 v[36:39], v123 offset:4096
	s_waitcnt lgkmcnt(2)
	v_mfma_f32_16x16x32_f16 v[56:59], v[0:3], v[40:43], 0
	v_cvt_pkrtz_f16_f32 v67, v54, v55
	v_cvt_pkrtz_f16_f32 v66, v52, v53
	v_pk_max_f16 v67, v67, 0
	v_pk_max_f16 v66, v66, 0
	v_mfma_f32_16x16x32_f16 v[60:63], v[8:11], v[40:43], 0
	v_cvt_pkrtz_f16_f32 v65, v50, v51
	v_cvt_pkrtz_f16_f32 v64, v48, v49
	v_pk_max_f16 v65, v65, 0
	v_mfma_f32_16x16x32_f16 v[56:59], v[4:7], v[44:47], v[56:59]
	v_pk_max_f16 v64, v64, 0
	v_mfma_f32_16x16x32_f16 v[60:63], v[12:15], v[44:47], v[60:63]
	s_nop 3
	v_mfma_f32_16x16x32_f16 v[68:71], v[80:83], v[64:67], v[84:87]
	ds_read_b128 v[40:43], v122 offset:6144
	ds_read_b128 v[44:47], v123 offset:6144
	s_waitcnt lgkmcnt(2)
	v_mfma_f32_16x16x32_f16 v[48:51], v[0:3], v[32:35], 0
	v_cvt_pkrtz_f16_f32 v67, v62, v63
	v_cvt_pkrtz_f16_f32 v66, v60, v61
	v_pk_max_f16 v67, v67, 0
	v_pk_max_f16 v66, v66, 0
	v_mfma_f32_16x16x32_f16 v[52:55], v[8:11], v[32:35], 0
	v_cvt_pkrtz_f16_f32 v65, v58, v59
	v_cvt_pkrtz_f16_f32 v64, v56, v57
	v_med3_f32 v76, v68, 0, v79
	v_pk_max_f16 v65, v65, 0
	v_mfma_f32_16x16x32_f16 v[48:51], v[4:7], v[36:39], v[48:51]
	v_pk_max_f16 v64, v64, 0
	v_cvt_u32_f32_e32 v76, v76
	v_mfma_f32_16x16x32_f16 v[52:55], v[12:15], v[36:39], v[52:55]
	v_lshl_add_u32 v77, v76, 2, v139
	s_nop 0
	ds_add_u32 v77, v212
	s_nop 0
	s_nop 0
	v_mfma_f32_16x16x32_f16 v[72:75], v[80:83], v[64:67], v[84:87]
	ds_read_b128 v[32:35], v122 offset:8192
	ds_read_b128 v[36:39], v123 offset:8192
	s_waitcnt lgkmcnt(3)
	v_mfma_f32_16x16x32_f16 v[56:59], v[0:3], v[40:43], 0
	v_cvt_pkrtz_f16_f32 v67, v54, v55
	v_cvt_pkrtz_f16_f32 v66, v52, v53
	v_pk_max_f16 v67, v67, 0
	v_pk_max_f16 v66, v66, 0
	v_mfma_f32_16x16x32_f16 v[60:63], v[8:11], v[40:43], 0
	v_cvt_pkrtz_f16_f32 v65, v50, v51
	v_cvt_pkrtz_f16_f32 v64, v48, v49
	v_med3_f32 v76, v72, 0, v79
	v_pk_max_f16 v65, v65, 0
	v_mfma_f32_16x16x32_f16 v[56:59], v[4:7], v[44:47], v[56:59]
	v_pk_max_f16 v64, v64, 0
	v_cvt_u32_f32_e32 v76, v76
	v_mfma_f32_16x16x32_f16 v[60:63], v[12:15], v[44:47], v[60:63]
	v_lshl_add_u32 v77, v76, 2, v139
	s_nop 0
	ds_add_u32 v77, v212
	s_nop 0
	s_nop 0
	v_mfma_f32_16x16x32_f16 v[68:71], v[80:83], v[64:67], v[84:87]
	ds_read_b128 v[40:43], v122 offset:10240
	ds_read_b128 v[44:47], v123 offset:10240
	s_waitcnt lgkmcnt(3)
; template <int PASS> ...
;     ...
;         for (int e = 0; e < 8; ++e) { const unsigned char* tp = lp + (hb * 8 + e) * 2048; kf[e][0] = *(const h16x8*)(tp + ((fq ^ sw) << 4)); kf[e][1] = *(const h16x8*)(tp + (((fq + 4) ^ sw) << 4)); }
; #pragma unroll
;         for (int e = 0; e < 8; ++e) { const int T = Tbase + hb * 8 + e;
;             f32x4 a0 = (f32x4){0.f, 0.f, 0.f, 0.f}, a1 = a0;
;             a0 = __builtin_amdgcn_mfma_f32_16x16x32_f16(aq[0][0], kf[e][0], a0, 0, 0, 0); a0 = __builtin_amdgcn_mfma_f32_16x16x32_f16(aq[0][1], kf[e][1], a0, 0, 0, 0);
;             a1 = __builtin_amdgcn_mfma_f32_16x16x32_f16(aq[1][0], kf[e][0], a1, 0, 0, 0); a1 = __builtin_amdgcn_mfma_f32_16x16x32_f16(aq[1][1], kf[e][1], a1, 0, 0, 0);
;             const h16x2 z2 = (h16x2){(h16)0.f, (h16)0.f};
;             const h16x2 r0 = __builtin_elementwise_max(__builtin_bit_cast(h16x2, __builtin_amdgcn_cvt_pkrtz(a0[0], a0[1])), z2), r1 = __builtin_elementwise_max(__builtin_bit_cast(h16x2, __builtin_amdgcn_cvt_pkrtz(a0[2], a0[3])), z2);
;             const h16x2 r2 = __builtin_elementwise_max(__builtin_bit_cast(h16x2, __builtin_amdgcn_cvt_pkrtz(a1[0], a1[1])), z2), r3 = __builtin_elementwise_max(__builtin_bit_cast(h16x2, __builtin_amdgcn_cvt_pkrtz(a1[2], a1[3])), z2);
;             const float sa = __builtin_amdgcn_fdot2(r0, wp[0], __builtin_amdgcn_fdot2(r1, wp[1], __builtin_amdgcn_fdot2(r2, wp[2], __builtin_amdgcn_fdot2(r3, wp[3], 0.f, false), false), false), false);
;             const int key = 16 * T + fr;
;             if (key <= tq) {
;                 const unsigned bin = (unsigned)(int)fminf(fmaxf(sa * 32.f + 128.f, 0.f), 255.f);
;                 if (PASS == 1) { if (bin >= b0) atomicAdd(&myhist[fq * 256 + bin], 1u); }
	v_mfma_f32_16x16x32_f16 v[48:51], v[0:3], v[32:35], 0
	v_cvt_pkrtz_f16_f32 v67, v62, v63
	v_cvt_pkrtz_f16_f32 v66, v60, v61
	v_pk_max_f16 v67, v67, 0
	v_pk_max_f16 v66, v66, 0
	v_mfma_f32_16x16x32_f16 v[52:55], v[8:11], v[32:35], 0
	v_cvt_pkrtz_f16_f32 v65, v58, v59
	v_cvt_pkrtz_f16_f32 v64, v56, v57
	v_med3_f32 v76, v68, 0, v79
	v_pk_max_f16 v65, v65, 0
	v_mfma_f32_16x16x32_f16 v[48:51], v[4:7], v[36:39], v[48:51]
	v_pk_max_f16 v64, v64, 0
	v_cvt_u32_f32_e32 v76, v76
	v_mfma_f32_16x16x32_f16 v[52:55], v[12:15], v[36:39], v[52:55]
	v_lshl_add_u32 v77, v76, 2, v139
	s_nop 0
	ds_add_u32 v77, v212
	s_nop 0
	s_nop 0
	v_mfma_f32_16x16x32_f16 v[72:75], v[80:83], v[64:67], v[84:87]
	ds_read_b128 v[32:35], v122 offset:12288
	ds_read_b128 v[36:39], v123 offset:12288
	s_waitcnt lgkmcnt(3)
	v_mfma_f32_16x16x32_f16 v[56:59], v[0:3], v[40:43], 0
	v_cvt_pkrtz_f16_f32 v67, v54, v55
	v_cvt_pkrtz_f16_f32 v66, v52, v53
	v_pk_max_f16 v67, v67, 0
	v_pk_max_f16 v66, v66, 0
	v_mfma_f32_16x16x32_f16 v[60:63], v[8:11], v[40:43], 0
	v_cvt_pkrtz_f16_f32 v65, v50, v51
	v_cvt_pkrtz_f16_f32 v64, v48, v49
	v_med3_f32 v76, v72, 0, v79
	v_pk_max_f16 v65, v65, 0
	v_mfma_f32_16x16x32_f16 v[56:59], v[4:7], v[44:47], v[56:59]
	v_pk_max_f16 v64, v64, 0
	v_cvt_u32_f32_e32 v76, v76
	v_mfma_f32_16x16x32_f16 v[60:63], v[12:15], v[44:47], v[60:63]
	v_lshl_add_u32 v77, v76, 2, v139
	s_nop 0
	ds_add_u32 v77, v212
	s_nop 0
	s_nop 0
	v_mfma_f32_16x16x32_f16 v[68:71], v[80:83], v[64:67], v[84:87]
	ds_read_b128 v[40:43], v122 offset:14336
	ds_read_b128 v[44:47], v123 offset:14336
	s_waitcnt lgkmcnt(3)
	v_mfma_f32_16x16x32_f16 v[48:51], v[0:3], v[32:35], 0
	v_cvt_pkrtz_f16_f32 v67, v62, v63
	v_cvt_pkrtz_f16_f32 v66, v60, v61
	v_pk_max_f16 v67, v67, 0
	v_pk_max_f16 v66, v66, 0
	v_mfma_f32_16x16x32_f16 v[52:55], v[8:11], v[32:35], 0
	v_cvt_pkrtz_f16_f32 v65, v58, v59
	v_cvt_pkrtz_f16_f32 v64, v56, v57
	v_med3_f32 v76, v68, 0, v79
	v_pk_max_f16 v65, v65, 0
	v_mfma_f32_16x16x32_f16 v[48:51], v[4:7], v[36:39], v[48:51]
	v_pk_max_f16 v64, v64, 0
	v_cvt_u32_f32_e32 v76, v76
	v_mfma_f32_16x16x32_f16 v[52:55], v[12:15], v[36:39], v[52:55]
	v_lshl_add_u32 v77, v76, 2, v139
	s_nop 0
	ds_add_u32 v77, v212
	s_nop 0
	s_nop 0
	v_mfma_f32_16x16x32_f16 v[72:75], v[80:83], v[64:67], v[84:87]
	ds_read_b128 v[32:35], v122 offset:16384
	ds_read_b128 v[36:39], v123 offset:16384
	s_waitcnt lgkmcnt(3)
	v_mfma_f32_16x16x32_f16 v[56:59], v[0:3], v[40:43], 0
	v_cvt_pkrtz_f16_f32 v67, v54, v55
	v_cvt_pkrtz_f16_f32 v66, v52, v53
	v_pk_max_f16 v67, v67, 0
	v_pk_max_f16 v66, v66, 0
	v_mfma_f32_16x16x32_f16 v[60:63], v[8:11], v[40:43], 0
	v_cvt_pkrtz_f16_f32 v65, v50, v51
	v_cvt_pkrtz_f16_f32 v64, v48, v49
	v_med3_f32 v76, v72, 0, v79
	v_pk_max_f16 v65, v65, 0
	v_mfma_f32_16x16x32_f16 v[56:59], v[4:7], v[44:47], v[56:59]
	v_pk_max_f16 v64, v64, 0
	v_cvt_u32_f32_e32 v76, v76
	v_mfma_f32_16x16x32_f16 v[60:63], v[12:15], v[44:47], v[60:63]
	v_lshl_add_u32 v77, v76, 2, v139
	s_nop 0
	ds_add_u32 v77, v212
	s_nop 0
	s_nop 0
	v_mfma_f32_16x16x32_f16 v[68:71], v[80:83], v[64:67], v[84:87]
	ds_read_b128 v[40:43], v122 offset:18432
	ds_read_b128 v[44:47], v123 offset:18432
	s_waitcnt lgkmcnt(3)
	v_mfma_f32_16x16x32_f16 v[48:51], v[0:3], v[32:35], 0
	v_cvt_pkrtz_f16_f32 v67, v62, v63
	v_cvt_pkrtz_f16_f32 v66, v60, v61
	v_pk_max_f16 v67, v67, 0
	v_pk_max_f16 v66, v66, 0
	v_mfma_f32_16x16x32_f16 v[52:55], v[8:11], v[32:35], 0
	v_cvt_pkrtz_f16_f32 v65, v58, v59
	v_cvt_pkrtz_f16_f32 v64, v56, v57
	v_med3_f32 v76, v68, 0, v79
	v_pk_max_f16 v65, v65, 0
	v_mfma_f32_16x16x32_f16 v[48:51], v[4:7], v[36:39], v[48:51]
	v_pk_max_f16 v64, v64, 0
	v_cvt_u32_f32_e32 v76, v76
	v_mfma_f32_16x16x32_f16 v[52:55], v[12:15], v[36:39], v[52:55]
	v_lshl_add_u32 v77, v76, 2, v139
	s_nop 0
	ds_add_u32 v77, v212
	s_nop 0
	s_nop 0
	v_mfma_f32_16x16x32_f16 v[72:75], v[80:83], v[64:67], v[84:87]
	ds_read_b128 v[32:35], v122 offset:20480
	ds_read_b128 v[36:39], v123 offset:20480
	s_waitcnt lgkmcnt(3)
	v_mfma_f32_16x16x32_f16 v[56:59], v[0:3], v[40:43], 0
	v_cvt_pkrtz_f16_f32 v67, v54, v55
	v_cvt_pkrtz_f16_f32 v66, v52, v53
	v_pk_max_f16 v67, v67, 0
	v_pk_max_f16 v66, v66, 0
	v_mfma_f32_16x16x32_f16 v[60:63], v[8:11], v[40:43], 0
	v_cvt_pkrtz_f16_f32 v65, v50, v51
	v_cvt_pkrtz_f16_f32 v64, v48, v49
	v_med3_f32 v76, v72, 0, v79
	v_pk_max_f16 v65, v65, 0
	v_mfma_f32_16x16x32_f16 v[56:59], v[4:7], v[44:47], v[56:59]
	v_pk_max_f16 v64, v64, 0
	v_cvt_u32_f32_e32 v76, v76
	v_mfma_f32_16x16x32_f16 v[60:63], v[12:15], v[44:47], v[60:63]
	v_lshl_add_u32 v77, v76, 2, v139
	s_nop 0
	ds_add_u32 v77, v212
	s_nop 0
	s_nop 0
	v_mfma_f32_16x16x32_f16 v[68:71], v[80:83], v[64:67], v[84:87]
	ds_read_b128 v[40:43], v122 offset:22528
	ds_read_b128 v[44:47], v123 offset:22528
	s_waitcnt lgkmcnt(3)
; template <int PASS> ...
;     ...
;         for (int e = 0; e < 8; ++e) { const unsigned char* tp = lp + (hb * 8 + e) * 2048; kf[e][0] = *(const h16x8*)(tp + ((fq ^ sw) << 4)); kf[e][1] = *(const h16x8*)(tp + (((fq + 4) ^ sw) << 4)); }
; #pragma unroll
;         for (int e = 0; e < 8; ++e) { const int T = Tbase + hb * 8 + e;
;             f32x4 a0 = (f32x4){0.f, 0.f, 0.f, 0.f}, a1 = a0;
;             a0 = __builtin_amdgcn_mfma_f32_16x16x32_f16(aq[0][0], kf[e][0], a0, 0, 0, 0); a0 = __builtin_amdgcn_mfma_f32_16x16x32_f16(aq[0][1], kf[e][1], a0, 0, 0, 0);
;             a1 = __builtin_amdgcn_mfma_f32_16x16x32_f16(aq[1][0], kf[e][0], a1, 0, 0, 0); a1 = __builtin_amdgcn_mfma_f32_16x16x32_f16(aq[1][1], kf[e][1], a1, 0, 0, 0);
;             const h16x2 z2 = (h16x2){(h16)0.f, (h16)0.f};
;             const h16x2 r0 = __builtin_elementwise_max(__builtin_bit_cast(h16x2, __builtin_amdgcn_cvt_pkrtz(a0[0], a0[1])), z2), r1 = __builtin_elementwise_max(__builtin_bit_cast(h16x2, __builtin_amdgcn_cvt_pkrtz(a0[2], a0[3])), z2);
;             const h16x2 r2 = __builtin_elementwise_max(__builtin_bit_cast(h16x2, __builtin_amdgcn_cvt_pkrtz(a1[0], a1[1])), z2), r3 = __builtin_elementwise_max(__builtin_bit_cast(h16x2, __builtin_amdgcn_cvt_pkrtz(a1[2], a1[3])), z2);
;             const float sa = __builtin_amdgcn_fdot2(r0, wp[0], __builtin_amdgcn_fdot2(r1, wp[1], __builtin_amdgcn_fdot2(r2, wp[2], __builtin_amdgcn_fdot2(r3, wp[3], 0.f, false), false), false), false);
;             const int key = 16 * T + fr;
;             if (key <= tq) {
;                 const unsigned bin = (unsigned)(int)fminf(fmaxf(sa * 32.f + 128.f, 0.f), 255.f);
;                 if (PASS == 1) { if (bin >= b0) atomicAdd(&myhist[fq * 256 + bin], 1u); }
	v_mfma_f32_16x16x32_f16 v[48:51], v[0:3], v[32:35], 0
	v_cvt_pkrtz_f16_f32 v67, v62, v63
	v_cvt_pkrtz_f16_f32 v66, v60, v61
	v_pk_max_f16 v67, v67, 0
	v_pk_max_f16 v66, v66, 0
	v_mfma_f32_16x16x32_f16 v[52:55], v[8:11], v[32:35], 0
	v_cvt_pkrtz_f16_f32 v65, v58, v59
	v_cvt_pkrtz_f16_f32 v64, v56, v57
	v_med3_f32 v76, v68, 0, v79
	v_pk_max_f16 v65, v65, 0
	v_mfma_f32_16x16x32_f16 v[48:51], v[4:7], v[36:39], v[48:51]
	v_pk_max_f16 v64, v64, 0
	v_cvt_u32_f32_e32 v76, v76
	v_mfma_f32_16x16x32_f16 v[52:55], v[12:15], v[36:39], v[52:55]
	v_lshl_add_u32 v77, v76, 2, v139
	s_nop 0
	ds_add_u32 v77, v212
	s_nop 0
	s_nop 0
	v_mfma_f32_16x16x32_f16 v[72:75], v[80:83], v[64:67], v[84:87]
	ds_read_b128 v[32:35], v122 offset:24576
	ds_read_b128 v[36:39], v123 offset:24576
	s_waitcnt lgkmcnt(3)
	v_mfma_f32_16x16x32_f16 v[56:59], v[0:3], v[40:43], 0
	v_cvt_pkrtz_f16_f32 v67, v54, v55
	v_cvt_pkrtz_f16_f32 v66, v52, v53
	v_pk_max_f16 v67, v67, 0
	v_pk_max_f16 v66, v66, 0
	v_mfma_f32_16x16x32_f16 v[60:63], v[8:11], v[40:43], 0
	v_cvt_pkrtz_f16_f32 v65, v50, v51
	v_cvt_pkrtz_f16_f32 v64, v48, v49
	v_med3_f32 v76, v72, 0, v79
	v_pk_max_f16 v65, v65, 0
	v_mfma_f32_16x16x32_f16 v[56:59], v[4:7], v[44:47], v[56:59]
	v_pk_max_f16 v64, v64, 0
	v_cvt_u32_f32_e32 v76, v76
	v_mfma_f32_16x16x32_f16 v[60:63], v[12:15], v[44:47], v[60:63]
	v_lshl_add_u32 v77, v76, 2, v139
	s_nop 0
	ds_add_u32 v77, v212
	s_nop 0
	s_nop 0
	v_mfma_f32_16x16x32_f16 v[68:71], v[80:83], v[64:67], v[84:87]
	ds_read_b128 v[40:43], v122 offset:26624
	ds_read_b128 v[44:47], v123 offset:26624
	s_waitcnt lgkmcnt(3)
	v_mfma_f32_16x16x32_f16 v[48:51], v[0:3], v[32:35], 0
	v_cvt_pkrtz_f16_f32 v67, v62, v63
	v_cvt_pkrtz_f16_f32 v66, v60, v61
	v_pk_max_f16 v67, v67, 0
	v_pk_max_f16 v66, v66, 0
	v_mfma_f32_16x16x32_f16 v[52:55], v[8:11], v[32:35], 0
	v_cvt_pkrtz_f16_f32 v65, v58, v59
	v_cvt_pkrtz_f16_f32 v64, v56, v57
	v_med3_f32 v76, v68, 0, v79
	v_pk_max_f16 v65, v65, 0
	v_mfma_f32_16x16x32_f16 v[48:51], v[4:7], v[36:39], v[48:51]
	v_pk_max_f16 v64, v64, 0
	v_cvt_u32_f32_e32 v76, v76
	v_mfma_f32_16x16x32_f16 v[52:55], v[12:15], v[36:39], v[52:55]
	v_lshl_add_u32 v77, v76, 2, v139
	s_nop 0
	ds_add_u32 v77, v212
	s_nop 0
	s_nop 0
	v_mfma_f32_16x16x32_f16 v[72:75], v[80:83], v[64:67], v[84:87]
	ds_read_b128 v[32:35], v122 offset:28672
	ds_read_b128 v[36:39], v123 offset:28672
	s_waitcnt lgkmcnt(3)
	v_mfma_f32_16x16x32_f16 v[56:59], v[0:3], v[40:43], 0
	v_cvt_pkrtz_f16_f32 v67, v54, v55
	v_cvt_pkrtz_f16_f32 v66, v52, v53
	v_pk_max_f16 v67, v67, 0
	v_pk_max_f16 v66, v66, 0
	v_mfma_f32_16x16x32_f16 v[60:63], v[8:11], v[40:43], 0
	v_cvt_pkrtz_f16_f32 v65, v50, v51
	v_cvt_pkrtz_f16_f32 v64, v48, v49
	v_med3_f32 v76, v72, 0, v79
	v_pk_max_f16 v65, v65, 0
	v_mfma_f32_16x16x32_f16 v[56:59], v[4:7], v[44:47], v[56:59]
	v_pk_max_f16 v64, v64, 0
	v_cvt_u32_f32_e32 v76, v76
	v_mfma_f32_16x16x32_f16 v[60:63], v[12:15], v[44:47], v[60:63]
	v_lshl_add_u32 v77, v76, 2, v139
	s_nop 0
	ds_add_u32 v77, v212
	s_nop 0
	s_nop 0
	v_mfma_f32_16x16x32_f16 v[68:71], v[80:83], v[64:67], v[84:87]
	ds_read_b128 v[40:43], v122 offset:30720
	ds_read_b128 v[44:47], v123 offset:30720
	s_waitcnt lgkmcnt(3)
	v_mfma_f32_16x16x32_f16 v[48:51], v[0:3], v[32:35], 0
	v_cvt_pkrtz_f16_f32 v67, v62, v63
	v_cvt_pkrtz_f16_f32 v66, v60, v61
	v_pk_max_f16 v67, v67, 0
	v_pk_max_f16 v66, v66, 0
	v_mfma_f32_16x16x32_f16 v[52:55], v[8:11], v[32:35], 0
	v_cvt_pkrtz_f16_f32 v65, v58, v59
	v_cvt_pkrtz_f16_f32 v64, v56, v57
	v_med3_f32 v76, v68, 0, v79
	v_pk_max_f16 v65, v65, 0
	v_mfma_f32_16x16x32_f16 v[48:51], v[4:7], v[36:39], v[48:51]
	v_pk_max_f16 v64, v64, 0
	v_cvt_u32_f32_e32 v76, v76
	v_mfma_f32_16x16x32_f16 v[52:55], v[12:15], v[36:39], v[52:55]
	v_lshl_add_u32 v77, v76, 2, v139
	s_nop 0
	ds_add_u32 v77, v212
	s_nop 0
	s_nop 0
	v_mfma_f32_16x16x32_f16 v[72:75], v[80:83], v[64:67], v[84:87]
	s_nop 3
	s_waitcnt lgkmcnt(1)
	v_mfma_f32_16x16x32_f16 v[56:59], v[0:3], v[40:43], 0
	v_cvt_pkrtz_f16_f32 v67, v54, v55
	v_cvt_pkrtz_f16_f32 v66, v52, v53
	v_pk_max_f16 v67, v67, 0
	v_pk_max_f16 v66, v66, 0
	v_mfma_f32_16x16x32_f16 v[60:63], v[8:11], v[40:43], 0
	v_cvt_pkrtz_f16_f32 v65, v50, v51
	v_cvt_pkrtz_f16_f32 v64, v48, v49
	v_med3_f32 v76, v72, 0, v79
	v_pk_max_f16 v65, v65, 0
	v_mfma_f32_16x16x32_f16 v[56:59], v[4:7], v[44:47], v[56:59]
	v_pk_max_f16 v64, v64, 0
	v_cvt_u32_f32_e32 v76, v76
	v_mfma_f32_16x16x32_f16 v[60:63], v[12:15], v[44:47], v[60:63]
	v_lshl_add_u32 v77, v76, 2, v139
	s_nop 0
	ds_add_u32 v77, v212
	s_nop 0
	s_nop 0
	v_mfma_f32_16x16x32_f16 v[68:71], v[80:83], v[64:67], v[84:87]
	s_nop 3
	v_cvt_pkrtz_f16_f32 v67, v62, v63
	v_cvt_pkrtz_f16_f32 v66, v60, v61
	v_pk_max_f16 v67, v67, 0
	v_pk_max_f16 v66, v66, 0
	v_cvt_pkrtz_f16_f32 v65, v58, v59
	v_cvt_pkrtz_f16_f32 v64, v56, v57
	v_med3_f32 v76, v68, 0, v79
	v_pk_max_f16 v65, v65, 0
	v_pk_max_f16 v64, v64, 0
	v_cvt_u32_f32_e32 v76, v76
	v_lshl_add_u32 v77, v76, 2, v139
	s_nop 0
	ds_add_u32 v77, v212
	s_nop 0
	s_nop 0
	v_mfma_f32_16x16x32_f16 v[72:75], v[80:83], v[64:67], v[84:87]
	s_nop 7
	s_nop 3
	v_med3_f32 v76, v72, 0, v79
	v_cvt_u32_f32_e32 v76, v76
	v_lshl_add_u32 v77, v76, 2, v139
	s_nop 0
	ds_add_u32 v77, v212
	s_nop 0
	s_nop 0
	s_branch .LBB0_239

; template <int PASS> ...
;     ...
;         for (int e = 0; e < 8; ++e) { const int T = Tbase + hb * 8 + e;
;             f32x4 a0 = (f32x4){0.f, 0.f, 0.f, 0.f}, a1 = a0;
;             a0 = __builtin_amdgcn_mfma_f32_16x16x32_f16(aq[0][0], kf[e][0], a0, 0, 0, 0); a0 = __builtin_amdgcn_mfma_f32_16x16x32_f16(aq[0][1], kf[e][1], a0, 0, 0, 0);
;             a1 = __builtin_amdgcn_mfma_f32_16x16x32_f16(aq[1][0], kf[e][0], a1, 0, 0, 0); a1 = __builtin_amdgcn_mfma_f32_16x16x32_f16(aq[1][1], kf[e][1], a1, 0, 0, 0);
;             const h16x2 z2 = (h16x2){(h16)0.f, (h16)0.f};
;             const h16x2 r0 = __builtin_elementwise_max(__builtin_bit_cast(h16x2, __builtin_amdgcn_cvt_pkrtz(a0[0], a0[1])), z2), r1 = __builtin_elementwise_max(__builtin_bit_cast(h16x2, __builtin_amdgcn_cvt_pkrtz(a0[2], a0[3])), z2);
;             const h16x2 r2 = __builtin_elementwise_max(__builtin_bit_cast(h16x2, __builtin_amdgcn_cvt_pkrtz(a1[0], a1[1])), z2), r3 = __builtin_elementwise_max(__builtin_bit_cast(h16x2, __builtin_amdgcn_cvt_pkrtz(a1[2], a1[3])), z2);
;             const float sa = __builtin_amdgcn_fdot2(r0, wp[0], __builtin_amdgcn_fdot2(r1, wp[1], __builtin_amdgcn_fdot2(r2, wp[2], __builtin_amdgcn_fdot2(r3, wp[3], 0.f, false), false), false), false);
;             const int key = 16 * T + fr;
;             if (key <= tq) {
;                 const unsigned bin = (unsigned)(int)fminf(fmaxf(sa * 32.f + 128.f, 0.f), 255.f);
;                 if (PASS == 1) { if (bin >= b0) atomicAdd(&myhist[fq * 256 + bin], 1u); }
;                 else {
;                     if (bin > b0) { const unsigned pos = atomicAdd(&myctl[fq * 4 + 2], 1u); ((unsigned short*)myhist)[fq * 256 + (pos & 255u)] = (unsigned short)key; }
;                     else if (bin == b0) { const unsigned c = atomicAdd(&myctl[fq * 4 + 3], 1u);
; __device__ __forceinline__ void dsa_select(const h16* PROJ, unsigned short* IDX, int* CNT, unsigned char* shm, unsigned* bar, unsigned xcc, unsigned xrank) {
;     ...
;             float wv[8];
;             { const h16x8 w8 = *(const h16x8*)(PROJ + O_WI + (size_t)(tokbase + tq) * 8);
; #pragma unroll
;               for (int h = 0; h < 8; ++h) wv[h] = (float)w8[h] * 0.04419417382415922f; }
;             h16x2 wp[4];
; #pragma unroll
;             for (int h = 0; h < 4; ++h) { wp[h].x = (h16)wv[(h >> 1) * 4 + (h & 1) * 2]; wp[h].y = (h16)wv[(h >> 1) * 4 + (h & 1) * 2 + 1]; }
.LBB0_293:
	s_and_b32 s4, s85, 0x8000
	v_add_u32_e32 v72, s4, v134
	v_add_u32_e32 v118, v72, v135
	v_add_u32_e32 v119, v72, v136
	ds_read_b128 v[32:35], v118
	ds_read_b128 v[36:39], v119
	ds_read_b128 v[40:43], v118 offset:2048
	ds_read_b128 v[44:47], v119 offset:2048
	v_lshlrev_b32_e32 v116, 8, v116
	v_sub_u32_e32 v117, v121, v116
	v_sub_u32_e32 v93, v192, v117
	v_mov_b32_e32 v92, 0
	v_subrev_u32_e32 v122, 0x100, v117
	s_cmp_lg_u32 s84, 1
	s_cbranch_scc1 .Lp2_skipw
	v_cvt_f32_u32_e32 v94, v120
	v_cmp_eq_u32_e32 vcc, 0, v120
	v_add_f32_e32 v95, 1.0, v94
	v_mov_b32_e32 v123, 0xff800000
	s_nop 0
	v_cndmask_b32_e32 v94, v94, v123, vcc
	v_cmp_lt_u32_e32 vcc, 0xfe, v120
	v_mov_b32_e32 v123, 0x7f800000
	s_nop 0
	v_cndmask_b32_e32 v95, v95, v123, vcc
	v_bfrev_b32_e32 v123, 1
	v_mul_f32_e32 v202, v106, v106
	v_fmac_f32_e32 v202, v107, v107
	v_fmac_f32_e32 v202, v108, v108
	v_fmac_f32_e32 v202, v109, v109
	v_fmac_f32_e32 v202, v110, v110
	v_fmac_f32_e32 v202, v111, v111
	v_fmac_f32_e32 v202, v112, v112
	v_fmac_f32_e32 v202, v113, v113
	v_max_f32_e32 v202, 0x358637bd, v202
	v_rsq_f32_e32 v202, v202
	s_mov_b32 s60, 0x100001
	s_mov_b32 s61, 0x10000100
	v_mul_f32_e32 v202, 4.0, v202
	v_cvt_pkrtz_f16_f32 v202, v202, v202
	v_pk_mul_f16 v84, v193, v202
	v_pk_mul_f16 v85, v194, v202
	v_pk_mul_f16 v86, v195, v202
	v_pk_mul_f16 v87, v196, v202
	v_cndmask_b32_e64 v84, 0, v84, s[60:61]
	v_cndmask_b32_e64 v85, 0, v85, s[60:61]
	v_cndmask_b32_e64 v86, 0, v86, s[60:61]
	v_cndmask_b32_e64 v87, 0, v87, s[60:61]
	v_mov_b32_e32 v88, 0x43000000
	v_mov_b32_e32 v89, 0
	v_mov_b32_e32 v90, 0
	v_mov_b32_e32 v91, 0
.Lp2_skipw:
	v_cmp_le_i32_e32 vcc, 240, v93
	s_cmp_eq_u64 vcc, -1
	s_cbranch_scc1 .Lp2_interior
	s_waitcnt lgkmcnt(2)
	v_mfma_f32_16x16x32_f16 v[48:51], v[0:3], v[32:35], 0
	v_mfma_f32_16x16x32_f16 v[52:55], v[8:11], v[32:35], 0
	v_mfma_f32_16x16x32_f16 v[48:51], v[4:7], v[36:39], v[48:51]
	v_mfma_f32_16x16x32_f16 v[52:55], v[12:15], v[36:39], v[52:55]
	s_nop 3
	ds_read_b128 v[32:35], v118 offset:4096
	ds_read_b128 v[36:39], v119 offset:4096
	s_waitcnt lgkmcnt(2)
	v_mfma_f32_16x16x32_f16 v[56:59], v[0:3], v[40:43], 0
	v_cvt_pkrtz_f16_f32 v75, v54, v55
	v_cvt_pkrtz_f16_f32 v74, v52, v53
	v_pk_max_f16 v75, v75, 0
	v_pk_max_f16 v74, v74, 0
	v_mfma_f32_16x16x32_f16 v[60:63], v[8:11], v[40:43], 0
	v_cvt_pkrtz_f16_f32 v73, v50, v51
	v_cvt_pkrtz_f16_f32 v72, v48, v49
	v_pk_max_f16 v73, v73, 0
	v_mfma_f32_16x16x32_f16 v[56:59], v[4:7], v[44:47], v[56:59]
	v_pk_max_f16 v72, v72, 0
	v_mfma_f32_16x16x32_f16 v[60:63], v[12:15], v[44:47], v[60:63]
	s_nop 3
	v_mfma_f32_16x16x32_f16 v[76:79], v[84:87], v[72:75], v[88:91]
	ds_read_b128 v[40:43], v118 offset:6144
	ds_read_b128 v[44:47], v119 offset:6144
	s_waitcnt lgkmcnt(2)
	v_mfma_f32_16x16x32_f16 v[64:67], v[0:3], v[32:35], 0
	v_cvt_pkrtz_f16_f32 v75, v62, v63
	v_cvt_pkrtz_f16_f32 v74, v60, v61
	v_pk_max_f16 v75, v75, 0
	v_pk_max_f16 v74, v74, 0
	v_mfma_f32_16x16x32_f16 v[68:71], v[8:11], v[32:35], 0
	v_cvt_pkrtz_f16_f32 v73, v58, v59
	v_cvt_pkrtz_f16_f32 v72, v56, v57
	v_cmp_le_i32_e32 vcc, 0, v93
	v_pk_max_f16 v73, v73, 0
	v_mfma_f32_16x16x32_f16 v[64:67], v[4:7], v[36:39], v[64:67]
	v_pk_max_f16 v72, v72, 0
	v_cmp_le_f32_e64 s[60:61], v95, v76
	v_cmp_le_f32_e64 s[62:63], v94, v76
	v_mfma_f32_16x16x32_f16 v[68:71], v[12:15], v[36:39], v[68:71]
	v_mfma_f32_16x16x32_f16 v[80:83], v[84:87], v[72:75], v[88:91]
	s_and_b64 s[62:63], s[62:63], vcc
	s_and_b64 vcc, vcc, s[60:61]
	v_addc_co_u32_e32 v92, vcc, v92, v92, vcc
	s_andn2_b64 s[62:63], s[62:63], s[60:61]
	s_cbranch_scc1 .Lp2d_slow0

; template <int PASS> ...
;     ...
;         for (int e = 0; e < 8; ++e) { const int T = Tbase + hb * 8 + e;
;             f32x4 a0 = (f32x4){0.f, 0.f, 0.f, 0.f}, a1 = a0;
;             a0 = __builtin_amdgcn_mfma_f32_16x16x32_f16(aq[0][0], kf[e][0], a0, 0, 0, 0); a0 = __builtin_amdgcn_mfma_f32_16x16x32_f16(aq[0][1], kf[e][1], a0, 0, 0, 0);
;             a1 = __builtin_amdgcn_mfma_f32_16x16x32_f16(aq[1][0], kf[e][0], a1, 0, 0, 0); a1 = __builtin_amdgcn_mfma_f32_16x16x32_f16(aq[1][1], kf[e][1], a1, 0, 0, 0);
;             const h16x2 z2 = (h16x2){(h16)0.f, (h16)0.f};
;             const h16x2 r0 = __builtin_elementwise_max(__builtin_bit_cast(h16x2, __builtin_amdgcn_cvt_pkrtz(a0[0], a0[1])), z2), r1 = __builtin_elementwise_max(__builtin_bit_cast(h16x2, __builtin_amdgcn_cvt_pkrtz(a0[2], a0[3])), z2);
;             const h16x2 r2 = __builtin_elementwise_max(__builtin_bit_cast(h16x2, __builtin_amdgcn_cvt_pkrtz(a1[0], a1[1])), z2), r3 = __builtin_elementwise_max(__builtin_bit_cast(h16x2, __builtin_amdgcn_cvt_pkrtz(a1[2], a1[3])), z2);
;             const float sa = __builtin_amdgcn_fdot2(r0, wp[0], __builtin_amdgcn_fdot2(r1, wp[1], __builtin_amdgcn_fdot2(r2, wp[2], __builtin_amdgcn_fdot2(r3, wp[3], 0.f, false), false), false), false);
;             const int key = 16 * T + fr;
;             if (key <= tq) {
;                 const unsigned bin = (unsigned)(int)fminf(fmaxf(sa * 32.f + 128.f, 0.f), 255.f);
;                 if (PASS == 1) { if (bin >= b0) atomicAdd(&myhist[fq * 256 + bin], 1u); }
;                 else {
;                     if (bin > b0) { const unsigned pos = atomicAdd(&myctl[fq * 4 + 2], 1u); ((unsigned short*)myhist)[fq * 256 + (pos & 255u)] = (unsigned short)key; }
;                     else if (bin == b0) { const unsigned c = atomicAdd(&myctl[fq * 4 + 3], 1u);
.Lp2_interior:
	s_waitcnt lgkmcnt(2)
	v_mfma_f32_16x16x32_f16 v[48:51], v[0:3], v[32:35], 0
	v_mfma_f32_16x16x32_f16 v[52:55], v[8:11], v[32:35], 0
	v_mfma_f32_16x16x32_f16 v[48:51], v[4:7], v[36:39], v[48:51]
	v_mfma_f32_16x16x32_f16 v[52:55], v[12:15], v[36:39], v[52:55]
	s_nop 3
	ds_read_b128 v[32:35], v118 offset:4096
	ds_read_b128 v[36:39], v119 offset:4096
	s_waitcnt lgkmcnt(2)
	v_mfma_f32_16x16x32_f16 v[56:59], v[0:3], v[40:43], 0
	v_cvt_pkrtz_f16_f32 v75, v54, v55
	v_cvt_pkrtz_f16_f32 v74, v52, v53
	v_pk_max_f16 v75, v75, 0
	v_pk_max_f16 v74, v74, 0
	v_mfma_f32_16x16x32_f16 v[60:63], v[8:11], v[40:43], 0
	v_cvt_pkrtz_f16_f32 v73, v50, v51
	v_cvt_pkrtz_f16_f32 v72, v48, v49
	v_pk_max_f16 v73, v73, 0
	v_mfma_f32_16x16x32_f16 v[56:59], v[4:7], v[44:47], v[56:59]
	v_pk_max_f16 v72, v72, 0
	v_mfma_f32_16x16x32_f16 v[60:63], v[12:15], v[44:47], v[60:63]
	s_nop 3
	s_nop 1
	v_mfma_f32_16x16x32_f16 v[76:79], v[84:87], v[72:75], v[88:91]
	ds_read_b128 v[40:43], v118 offset:6144
	ds_read_b128 v[44:47], v119 offset:6144
	s_waitcnt lgkmcnt(2)
	v_mfma_f32_16x16x32_f16 v[64:67], v[0:3], v[32:35], 0
	v_cvt_pkrtz_f16_f32 v75, v62, v63
	v_cvt_pkrtz_f16_f32 v74, v60, v61
	v_pk_max_f16 v75, v75, 0
	v_pk_max_f16 v74, v74, 0
	v_mfma_f32_16x16x32_f16 v[68:71], v[8:11], v[32:35], 0
	v_cvt_pkrtz_f16_f32 v73, v58, v59
	v_cvt_pkrtz_f16_f32 v72, v56, v57
	v_pk_max_f16 v73, v73, 0
	v_mfma_f32_16x16x32_f16 v[64:67], v[4:7], v[36:39], v[64:67]
	v_pk_max_f16 v72, v72, 0
	v_cmp_le_f32_e64 s[62:63], v94, v76
	v_cmp_le_f32_e32 vcc, v95, v76
	v_mfma_f32_16x16x32_f16 v[68:71], v[12:15], v[36:39], v[68:71]
	s_nop 1
	v_mfma_f32_16x16x32_f16 v[80:83], v[84:87], v[72:75], v[88:91]
	s_andn2_b64 s[62:63], s[62:63], vcc
	v_addc_co_u32_e32 v92, vcc, v92, v92, vcc
	s_cmp_lg_u64 s[62:63], 0
	s_cbranch_scc1 .Lp2i_slow0
